# baseline (speedup 1.0000x reference)
; __device__ __forceinline__ bfr f2bf(float f) { return (bfr)(pk2(f, f) & 0xffffu); }
; __device__ __forceinline__ void mla_prep(const PRef& P) {
;     ...
;     const float other = __shfl_xor(kr, 32);
;     const float outv = lane < 32 ? (kr * cf - other * sf) : (other * sf + kr * cf);
;     const bfr ob = f2bf(outv); const int b = row >> 14, s = row & (SQ - 1);
; #pragma unroll
;     for (int h = 0; h < 8; ++h) Kb[(((long)(b * 8 + h)) * SQ + s) * 192 + 128 + lane] = ob;
;   }
.LBB0_1013:
	s_or_b64 exec, exec, s[8:9]
	ds_bpermute_b32 v25, v19, v126
	v_ashrrev_i32_e32 v30, 11, v18
	s_movk_i32 s2, 0x180
	s_waitcnt lgkmcnt(0)
	v_mul_f32_e32 v17, v17, v25
	v_cndmask_b32_e64 v17, v17, -v17, vcc
	v_fmac_f32_e32 v17, v126, v16
	v_and_b32_e32 v16, -8, v30
	v_cvt_pk_bf16_f32 v0, v17, v17
	v_ashrrev_i32_e32 v17, 31, v16
	v_and_b32_e32 v25, 0x3fff, v18
	v_lshlrev_b64 v[26:27], 14, v[16:17]
	v_or_b32_e32 v17, v26, v25
	v_mad_u64_u32 v[28:29], s[8:9], v17, s2, v[4:5]
	v_or_b32_e32 v26, 1, v16
	v_mad_i32_i24 v29, v27, s2, v29
	v_ashrrev_i32_e32 v27, 31, v26
	v_lshlrev_b64 v[26:27], 14, v[26:27]
	v_or_b32_e32 v17, v26, v25
	global_store_short v[28:29], v0, off
	v_mad_u64_u32 v[28:29], s[8:9], v17, s2, v[4:5]
	v_or_b32_e32 v26, 2, v16
	v_mad_i32_i24 v29, v27, s2, v29
	v_ashrrev_i32_e32 v27, 31, v26
	v_lshlrev_b64 v[26:27], 14, v[26:27]
	v_or_b32_e32 v17, v26, v25
	global_store_short v[28:29], v0, off
	v_mad_u64_u32 v[28:29], s[8:9], v17, s2, v[4:5]
	v_or_b32_e32 v26, 3, v16
	v_mad_i32_i24 v29, v27, s2, v29
	v_ashrrev_i32_e32 v27, 31, v26
	v_lshlrev_b64 v[26:27], 14, v[26:27]
	v_or_b32_e32 v17, v26, v25
	global_store_short v[28:29], v0, off
	v_mad_u64_u32 v[28:29], s[8:9], v17, s2, v[4:5]
	v_or_b32_e32 v26, 4, v16
	v_mad_i32_i24 v29, v27, s2, v29
	v_ashrrev_i32_e32 v27, 31, v26
	v_lshlrev_b64 v[26:27], 14, v[26:27]
	v_or_b32_e32 v17, v26, v25
	global_store_short v[28:29], v0, off
	v_mad_u64_u32 v[28:29], s[8:9], v17, s2, v[4:5]
	v_or_b32_e32 v26, 5, v16
	v_mad_i32_i24 v29, v27, s2, v29
	v_ashrrev_i32_e32 v27, 31, v26
	v_lshlrev_b64 v[26:27], 14, v[26:27]
	v_or_b32_e32 v17, v26, v25
	v_or_b32_e32 v16, 6, v16
	global_store_short v[28:29], v0, off
	v_mad_u64_u32 v[28:29], s[8:9], v17, s2, v[4:5]
	v_ashrrev_i32_e32 v17, 31, v16
	v_lshlrev_b64 v[16:17], 14, v[16:17]
	v_or_b32_e32 v16, v16, v25
	v_mad_i32_i24 v29, v27, s2, v29
	v_mad_u64_u32 v[26:27], s[8:9], v16, s2, v[4:5]
	v_or_b32_e32 v16, 7, v30
	v_mad_i32_i24 v27, v17, s2, v27
	v_ashrrev_i32_e32 v17, 31, v16
	v_lshlrev_b64 v[16:17], 14, v[16:17]
	v_or_b32_e32 v16, v16, v25
	global_store_short v[26:27], v0, off
	v_mad_u64_u32 v[26:27], s[8:9], v16, s2, v[4:5]
	v_readlane_b32 s8, v254, 29
	v_readlane_b32 s9, v254, 30
	v_mad_i32_i24 v27, v17, s2, v27
	v_add_u32_e32 v18, s90, v18
	v_lshl_add_u64 v[6:7], v[6:7], 0, s[8:9]
	v_readlane_b32 s8, v254, 31
	v_readlane_b32 s9, v254, 32
	s_movk_i32 s2, 0x7fff
	global_store_short v[28:29], v0, off
	v_lshl_add_u64 v[8:9], v[8:9], 0, s[8:9]
	v_readlane_b32 s8, v254, 33
	v_readlane_b32 s9, v254, 34
	global_store_short v[26:27], v0, off
	s_nop 0
	v_lshl_add_u64 v[10:11], v[10:11], 0, s[8:9]
	v_readlane_b32 s8, v254, 35
	v_readlane_b32 s9, v254, 36
	s_nop 1
	v_lshl_add_u64 v[12:13], v[12:13], 0, s[8:9]
	v_readlane_b32 s8, v254, 37
	v_readlane_b32 s9, v254, 38
	s_nop 1
	v_lshl_add_u64 v[14:15], v[14:15], 0, s[8:9]
	v_cmp_lt_i32_e64 s[8:9], s2, v18
	s_or_b64 s[14:15], s[8:9], s[14:15]
	s_andn2_b64 exec, exec, s[14:15]
	s_cbranch_execz .LBB0_1026
; __device__ __forceinline__ bfr f2bf(float f) { return (bfr)(pk2(f, f) & 0xffffu); }
; __device__ __forceinline__ void mla_prep(const PRef& P) {
;     ...
;   for (int row = wv; row < TT; row += nw) {
;     const float* lp = LAT + (long)row * 768; float ql[6], kl[4]; float sq = 0.f, sk = 0.f;
; #pragma unroll
;     for (int i = 0; i < 6; ++i) { ql[i] = lp[lane + 64 * i]; sq += ql[i] * ql[i]; }
; #pragma unroll
;     for (int i = 0; i < 4; ++i) { kl[i] = lp[384 + lane + 64 * i]; sk += kl[i] * kl[i]; }
;     float kr = lp[640 + lane];
; #pragma unroll
;     for (int o = 32; o > 0; o >>= 1) { sq += __shfl_xor(sq, o); sk += __shfl_xor(sk, o); }
;     const float rq = rsqrtf(sq * (1.f / 384) + 1e-6f), rk = rsqrtf(sk * (1.f / 256) + 1e-6f);
; #pragma unroll
;     for (int i = 0; i < 6; ++i) qn[(long)row * 384 + lane + 64 * i] = f2bf(ql[i] * rq);
; #pragma unroll
;     for (int i = 0; i < 4; ++i) kvn[(long)row * 256 + lane + 64 * i] = f2bf(kl[i] * rk);
;     float sf, cf; rsincos((double)pos[row] * invf, sf, cf);
.LBB0_1014:
	global_load_dword v16, v[10:11], off offset:-768
	global_load_dword v17, v[10:11], off offset:-512
	global_load_dword v26, v[10:11], off offset:-256
	global_load_dword v27, v[10:11], off
	global_load_dword v28, v[10:11], off offset:256
	global_load_dword v29, v[10:11], off offset:512
	global_load_dword v30, v[10:11], off offset:768
	global_load_dword v31, v[10:11], off offset:1024
	global_load_dword v33, v[10:11], off offset:-1024
	global_load_dword v32, v[10:11], off offset:-1280
	global_load_dword v125, v[8:9], off
	global_load_dword v126, v[10:11], off offset:1280
	v_and_b32_e32 v120, 63, v182
	v_mul_u32_u24_e32 v120, 40, v120
	v_add_u32_e32 v120, 0x5ffb00, v120
	v_mov_b32_e32 v121, 0
	v_lshl_add_u64 v[122:123], v[10:11], 0, v[120:121]
	global_load_dword v124, v[122:123], off
	s_mov_b32 s8, 0x3b800000
	s_mov_b32 s9, 0x3b2aaaab
	s_waitcnt vmcnt(1)
	v_pk_mul_f32 v[34:35], v[16:17], v[16:17]
	v_pk_mul_f32 v[36:37], v[26:27], v[26:27]
	s_nop 0
	v_mov_b32_e32 v45, v36
	v_pk_mul_f32 v[38:39], v[28:29], v[28:29]
	v_pk_mul_f32 v[40:41], v[30:31], v[30:31]
	v_mul_f32_e32 v0, v33, v33
	v_pk_fma_f32 v[42:43], v[32:33], v[32:33], v[0:1] op_sel_hi:[1,1,0]
	v_mov_b32_e32 v44, v40
	v_mov_b32_e32 v36, v41
	v_pk_fma_f32 v[40:41], v[16:17], v[16:17], v[42:43]
	v_mov_b32_e32 v34, v39
	v_mov_b32_e32 v39, v40
	v_pk_add_f32 v[34:35], v[38:39], v[34:35]
	s_nop 0
	v_pk_add_f32 v[34:35], v[34:35], v[44:45]
	s_nop 0
	v_pk_add_f32 v[34:35], v[34:35], v[36:37]
	ds_bpermute_b32 v37, v19, v35
	ds_bpermute_b32 v36, v19, v34
	s_waitcnt lgkmcnt(0)
	v_pk_add_f32 v[34:35], v[34:35], v[36:37]
	ds_bpermute_b32 v37, v20, v35
	ds_bpermute_b32 v36, v20, v34
	s_waitcnt lgkmcnt(0)
	v_pk_add_f32 v[34:35], v[34:35], v[36:37]
	ds_bpermute_b32 v37, v21, v35
	ds_bpermute_b32 v36, v21, v34
	s_waitcnt lgkmcnt(0)
	v_pk_add_f32 v[34:35], v[34:35], v[36:37]
	ds_bpermute_b32 v37, v22, v35
	ds_bpermute_b32 v36, v22, v34
	s_waitcnt lgkmcnt(0)
	v_pk_add_f32 v[34:35], v[34:35], v[36:37]
	ds_bpermute_b32 v37, v23, v35
	ds_bpermute_b32 v36, v23, v34
	s_waitcnt lgkmcnt(0)
	v_pk_add_f32 v[34:35], v[34:35], v[36:37]
	ds_bpermute_b32 v37, v24, v35
	ds_bpermute_b32 v36, v24, v34
	s_waitcnt lgkmcnt(0)
	v_pk_add_f32 v[34:35], v[34:35], v[36:37]
	s_nop 0
	v_pk_fma_f32 v[34:35], v[34:35], s[8:9], v[186:187] op_sel_hi:[1,1,0]
	s_nop 0
	v_mul_f32_e32 v0, 0x4b800000, v35
	v_mul_f32_e32 v25, 0x4b800000, v34
	v_cmp_gt_f32_e64 s[8:9], s7, v35
	v_cmp_gt_f32_e64 s[10:11], s7, v34
	s_nop 0
	v_cndmask_b32_e64 v0, v35, v0, s[8:9]
	v_cndmask_b32_e64 v25, v34, v25, s[10:11]
	v_rsq_f32_e32 v0, v0
	v_rsq_f32_e32 v25, v25
	v_mul_f32_e32 v34, 0x45800000, v0
	v_mul_f32_e32 v35, 0x45800000, v25
	v_cndmask_b32_e64 v0, v0, v34, s[8:9]
	v_cndmask_b32_e64 v25, v25, v35, s[10:11]
	v_mul_f32_e32 v32, v32, v0
	v_mul_f32_e32 v33, v33, v0
	v_mul_f32_e32 v16, v16, v0
	v_mul_f32_e32 v17, v17, v0
	v_mul_f32_e32 v26, v26, v0
	v_mul_f32_e32 v0, v27, v0
	v_mul_f32_e32 v27, v28, v25
	v_mul_f32_e32 v28, v29, v25
	v_mul_f32_e32 v29, v30, v25
	v_mul_f32_e32 v25, v31, v25
	v_cvt_pk_bf16_f32 v30, v32, v32
	v_cvt_pk_bf16_f32 v31, v33, v33
	v_cvt_pk_bf16_f32 v16, v16, v16
	v_cvt_pk_bf16_f32 v17, v17, v17
	v_cvt_pk_bf16_f32 v26, v26, v26
	v_cvt_pk_bf16_f32 v0, v0, v0
	v_cvt_pk_bf16_f32 v27, v27, v27
	v_cvt_pk_bf16_f32 v28, v28, v28
	v_cvt_pk_bf16_f32 v29, v29, v29
	v_cvt_pk_bf16_f32 v25, v25, v25
	global_store_short v[14:15], v30, off offset:-384
	global_store_short v[14:15], v31, off offset:-256
	global_store_short v[14:15], v16, off offset:-128
	global_store_short v[14:15], v17, off
	global_store_short v[14:15], v26, off offset:128
	global_store_short v[14:15], v0, off offset:256
	global_store_short v[12:13], v27, off offset:-256
	global_store_short v[12:13], v28, off offset:-128
	global_store_short v[12:13], v29, off
	global_store_short v[12:13], v25, off offset:128
	s_mov_b32 s8, 0x6dc9c883
	s_mov_b32 s9, 0x3fe45f30
	v_cvt_f64_i32_e32 v[16:17], v125
	v_mul_f64 v[16:17], v[2:3], v[16:17]
	v_mul_f64 v[26:27], v[16:17], s[8:9]
	s_mov_b32 s8, 0x54442d18
	v_rndne_f64_e32 v[26:27], v[26:27]
	s_mov_b32 s9, 0xbff921fb
	v_fmac_f64_e32 v[16:17], s[8:9], v[26:27]
	s_mov_b32 s8, 0x33145c07
	s_mov_b32 s9, 0xbc91a626
	v_fmac_f64_e32 v[16:17], s[8:9], v[26:27]
	v_cvt_f32_f64_e32 v185, v[16:17]
	v_mul_f32_e32 v16, v185, v185
	v_cvt_i32_f64_e32 v25, v[26:27]
	v_fmamk_f32 v26, v16, 0xb493f27e, v187
	v_fmamk_f32 v17, v16, 0x3638ef1d, v183
	v_fmaak_f32 v26, v16, v26, 0xbab60b61
	v_fmaak_f32 v17, v16, v17, 0x3c088888
	v_fmaak_f32 v26, v16, v26, 0x3d2aaaab
	v_and_b32_e32 v25, 3, v25
	v_mul_f32_e32 v27, v16, v185
	v_fmaak_f32 v17, v16, v17, 0xbe2aaaab
	v_fma_f32 v26, v16, v26, -0.5
	v_pk_fma_f32 v[16:17], v[26:27], v[16:17], v[184:185]
	v_cmp_lt_i32_e64 s[8:9], 1, v25
	s_and_saveexec_b64 s[10:11], s[8:9]
	s_xor_b64 s[10:11], exec, s[10:11]
	s_cbranch_execz .LBB0_1021
	v_cmp_lt_i32_e64 s[8:9], 2, v25
	s_and_saveexec_b64 s[16:17], s[8:9]
	s_xor_b64 s[8:9], exec, s[16:17]
	v_xor_b32_e32 v25, 0x80000000, v16
	v_mov_b32_e32 v16, v17
	v_mov_b32_e32 v17, v25
	s_andn2_saveexec_b64 s[8:9], s[8:9]
	v_pk_add_f32 v[16:17], v[16:17], 0 neg_lo:[1,1] neg_hi:[1,1]
	s_or_b64 exec, exec, s[8:9]
	s_andn2_saveexec_b64 s[10:11], s[10:11]
	s_cbranch_execnz .LBB0_1022

; __device__ __forceinline__ bfr f2bf(float f) { return (bfr)(pk2(f, f) & 0xffffu); }
; __device__ __forceinline__ void mla_prep(const PRef& P) {
;     ...
;   for (int row = wv; row < TT; row += nw) {
;     const float* lp = LAT + (long)row * 768; float ql[6], kl[4]; float sq = 0.f, sk = 0.f;
; #pragma unroll
;     for (int i = 0; i < 6; ++i) { ql[i] = lp[lane + 64 * i]; sq += ql[i] * ql[i]; }
; #pragma unroll
;     for (int i = 0; i < 4; ++i) { kl[i] = lp[384 + lane + 64 * i]; sk += kl[i] * kl[i]; }
;     float kr = lp[640 + lane];
; #pragma unroll
;     for (int o = 32; o > 0; o >>= 1) { sq += __shfl_xor(sq, o); sk += __shfl_xor(sk, o); }
;     const float rq = rsqrtf(sq * (1.f / 384) + 1e-6f), rk = rsqrtf(sk * (1.f / 256) + 1e-6f);
; #pragma unroll
;     for (int i = 0; i < 6; ++i) qn[(long)row * 384 + lane + 64 * i] = f2bf(ql[i] * rq);
; #pragma unroll
;     for (int i = 0; i < 4; ++i) kvn[(long)row * 256 + lane + 64 * i] = f2bf(kl[i] * rk);
;     float sf, cf; rsincos((double)pos[row] * invf, sf, cf);
;     if (lane < 32) rope[(long)row * 32 + lane] = make_float2(cf, sf);
;     const float other = __shfl_xor(kr, 32);
;     const float outv = lane < 32 ? (kr * cf - other * sf) : (other * sf + kr * cf);
;     const bfr ob = f2bf(outv); const int b = row >> 14, s = row & (SQ - 1);
; #pragma unroll
;     for (int h = 0; h < 8; ++h) Kb[(((long)(b * 8 + h)) * SQ + s) * 192 + 128 + lane] = ob;
;   }
.LBB0_1026:
	s_waitcnt vmcnt(0)
	s_or_b64 exec, exec, s[12:13]
